# v047_nt
# speedup vs baseline: 1.0079x; 1.0079x over previous
.LBB0_155:
	s_waitcnt vmcnt(2)
	v_lshl_add_u64 v[28:29], v[34:35], 4, s[4:5]
	s_waitcnt lgkmcnt(0)
	s_lshl_b64 s[4:5], s[16:17], 12
	v_lshl_add_u64 v[32:33], v[4:5], 0, s[4:5]
	v_add_co_u32_e64 v44, s[4:5], s2, v28
	global_load_dwordx4 v[12:15], v[28:29], off nt
	global_load_dwordx4 v[16:19], v[28:29], off offset:1024 nt
	v_addc_co_u32_e64 v45, s[4:5], 0, v29, s[4:5]
	global_load_dwordx4 v[20:23], v[28:29], off offset:2048 nt
	global_load_dwordx4 v[24:27], v[28:29], off offset:3072 nt
	global_load_dwordx4 v[48:51], v[44:45], off nt
	global_load_dwordx4 v[36:39], v[44:45], off offset:1024 nt
	global_load_dwordx4 v[40:43], v[44:45], off offset:2048 nt
	global_load_dwordx4 v[52:55], v[44:45], off offset:3072 nt
	s_waitcnt vmcnt(7)
	v_cvt_pk_bf16_f32 v56, v12, v13
	v_cvt_pk_bf16_f32 v57, v14, v15
	global_store_dwordx2 v[32:33], v[56:57], off
	v_mul_f32_e32 v13, v13, v13
	v_mul_f32_e32 v15, v15, v15
	v_fmac_f32_e32 v13, v12, v12
	v_fmac_f32_e32 v15, v14, v14
	v_add_f32_e32 v12, v13, v15
	s_waitcnt vmcnt(7)
	v_cvt_pk_bf16_f32 v58, v16, v17
	v_cvt_pk_bf16_f32 v59, v18, v19
	global_store_dwordx2 v[32:33], v[58:59], off offset:512
	v_mul_f32_e32 v13, v17, v17
	v_mul_f32_e32 v14, v19, v19
	v_fmac_f32_e32 v13, v16, v16
	v_fmac_f32_e32 v14, v18, v18
	v_add_f32_e32 v13, v13, v14
	v_add_f32_e32 v12, v12, v13
	s_waitcnt vmcnt(7)
	v_cvt_pk_bf16_f32 v60, v20, v21
	v_cvt_pk_bf16_f32 v61, v22, v23
	global_store_dwordx2 v[32:33], v[60:61], off offset:1024
	v_mul_f32_e32 v13, v21, v21
	v_mul_f32_e32 v14, v23, v23
	v_fmac_f32_e32 v13, v20, v20
	v_fmac_f32_e32 v14, v22, v22
	v_add_f32_e32 v13, v13, v14
	v_add_f32_e32 v12, v12, v13
	s_waitcnt vmcnt(7)
	v_cvt_pk_bf16_f32 v62, v24, v25
	v_cvt_pk_bf16_f32 v63, v26, v27
	global_store_dwordx2 v[32:33], v[62:63], off offset:1536
	v_mul_f32_e32 v13, v25, v25
	v_mul_f32_e32 v14, v27, v27
	v_fmac_f32_e32 v13, v24, v24
	v_fmac_f32_e32 v14, v26, v26
	v_add_f32_e32 v13, v13, v14
	v_add_f32_e32 v12, v12, v13
	s_waitcnt vmcnt(7)
	v_cvt_pk_bf16_f32 v64, v48, v49
	v_cvt_pk_bf16_f32 v65, v50, v51
	global_store_dwordx2 v[32:33], v[64:65], off offset:2048
	v_mul_f32_e32 v13, v49, v49
	v_mul_f32_e32 v14, v51, v51
	v_fmac_f32_e32 v13, v48, v48
	v_fmac_f32_e32 v14, v50, v50
	v_add_f32_e32 v13, v13, v14
	v_add_f32_e32 v12, v12, v13
	s_waitcnt vmcnt(7)
	v_cvt_pk_bf16_f32 v66, v36, v37
	v_cvt_pk_bf16_f32 v67, v38, v39
	global_store_dwordx2 v[32:33], v[66:67], off offset:2560
	v_mul_f32_e32 v13, v37, v37
	v_mul_f32_e32 v14, v39, v39
	v_fmac_f32_e32 v13, v36, v36
	v_fmac_f32_e32 v14, v38, v38
	v_add_f32_e32 v13, v13, v14
	v_add_f32_e32 v12, v12, v13
	s_waitcnt vmcnt(7)
	v_cvt_pk_bf16_f32 v68, v40, v41
	v_cvt_pk_bf16_f32 v69, v42, v43
	global_store_dwordx2 v[32:33], v[68:69], off offset:3072
	v_mul_f32_e32 v13, v41, v41
	v_mul_f32_e32 v14, v43, v43
	v_fmac_f32_e32 v13, v40, v40
	v_fmac_f32_e32 v14, v42, v42
	v_add_f32_e32 v13, v13, v14
	v_add_f32_e32 v12, v12, v13
	s_waitcnt vmcnt(7)
	v_cvt_pk_bf16_f32 v70, v52, v53
	v_cvt_pk_bf16_f32 v71, v54, v55
	global_store_dwordx2 v[32:33], v[70:71], off offset:3584
	v_mul_f32_e32 v13, v53, v53
	v_mul_f32_e32 v14, v55, v55
	v_fmac_f32_e32 v13, v52, v52
	v_fmac_f32_e32 v14, v54, v54
	v_add_f32_e32 v13, v13, v14
	v_add_f32_e32 v12, v12, v13
	ds_bpermute_b32 v13, v1, v12
	s_waitcnt lgkmcnt(0)
	v_add_f32_e32 v12, v12, v13
	ds_bpermute_b32 v13, v7, v12
	s_waitcnt lgkmcnt(0)
	v_add_f32_e32 v12, v12, v13
	ds_bpermute_b32 v13, v8, v12
	s_waitcnt lgkmcnt(0)
	v_add_f32_e32 v12, v12, v13
	ds_bpermute_b32 v13, v9, v12
	s_waitcnt lgkmcnt(0)
	v_add_f32_e32 v12, v12, v13
	ds_bpermute_b32 v13, v10, v12
	s_waitcnt lgkmcnt(0)
	v_add_f32_e32 v12, v12, v13
	ds_bpermute_b32 v13, v11, v12
	s_and_saveexec_b64 s[4:5], vcc
	s_cbranch_execz .LBB0_152
	s_waitcnt lgkmcnt(0)
	v_add_f32_e32 v12, v12, v13
	s_lshl_b64 s[16:17], s[16:17], 5
	v_cndmask_b32_e64 v14, 0, v12, s[0:1]
	v_lshl_add_u64 v[12:13], v[2:3], 0, s[16:17]
	global_store_dword v[12:13], v14, off
	s_branch .LBB0_152

.LBB0_633:
	s_or_b64 exec, exec, s[2:3]
	v_lshl_add_u64 v[30:31], s[48:49], 0, v[18:19]
	v_add_co_u32_e32 v42, vcc, s14, v30
	s_waitcnt vmcnt(0)
	ds_bpermute_b32 v29, v20, v28
	v_addc_co_u32_e32 v43, vcc, 0, v31, vcc
	global_load_dwordx4 v[30:33], v[42:43], off nt
	global_load_dwordx4 v[34:37], v[2:3], off
	global_load_dwordx4 v[38:41], v[2:3], off offset:16
	global_load_dwordx4 v[60:63], v[42:43], off offset:1024 nt
	global_load_dwordx4 v[64:67], v[6:7], off
	global_load_dwordx4 v[68:71], v[6:7], off offset:16
	global_load_dwordx4 v[72:75], v[42:43], off offset:2048 nt
	global_load_dwordx4 v[76:79], v[10:11], off
	global_load_dwordx4 v[80:83], v[10:11], off offset:16
	global_load_dwordx4 v[84:87], v[42:43], off offset:3072 nt
	global_load_dwordx4 v[88:91], v[14:15], off
	global_load_dwordx4 v[92:95], v[14:15], off offset:16
	s_waitcnt lgkmcnt(0)
	v_add_f32_e32 v28, v28, v29
	ds_bpermute_b32 v29, v21, v28
	s_add_i32 s4, s4, s18
	v_lshl_add_u64 v[16:17], v[16:17], 0, s[6:7]
	v_lshl_add_u64 v[18:19], v[18:19], 0, s[8:9]
	s_waitcnt lgkmcnt(0)
	v_add_f32_e32 v28, v28, v29
	ds_bpermute_b32 v29, v22, v28
	s_waitcnt lgkmcnt(0)
	v_add_f32_e32 v28, v28, v29
	ds_bpermute_b32 v29, v23, v28
	s_waitcnt lgkmcnt(0)
	v_add_f32_e32 v28, v28, v29
	ds_bpermute_b32 v29, v24, v28
	s_waitcnt lgkmcnt(0)
	v_add_f32_e32 v28, v28, v29
	ds_bpermute_b32 v29, v25, v28
	s_waitcnt lgkmcnt(0)
	v_add_f32_e32 v28, v28, v29
	v_fmamk_f32 v28, v28, 0x3a000000, v26
	v_mul_f32_e32 v29, 0x4f800000, v28
	v_cmp_gt_f32_e32 vcc, s5, v28
	s_nop 1
	v_cndmask_b32_e32 v28, v28, v29, vcc
	v_sqrt_f32_e32 v29, v28
	s_nop 0
	v_add_u32_e32 v44, -1, v29
	v_add_u32_e32 v45, 1, v29
	v_fma_f32 v46, -v44, v29, v28
	v_fma_f32 v47, -v45, v29, v28
	v_cmp_ge_f32_e64 s[2:3], 0, v46
	s_nop 1
	v_cndmask_b32_e64 v29, v29, v44, s[2:3]
	v_cmp_lt_f32_e64 s[2:3], 0, v47
	s_nop 1
	v_cndmask_b32_e64 v29, v29, v45, s[2:3]
	v_mul_f32_e32 v44, 0x37800000, v29
	v_cndmask_b32_e32 v29, v29, v44, vcc
	v_cmp_class_f32_e32 vcc, v28, v27
	v_lshl_add_u64 v[44:45], s[10:11], 0, v[0:1]
	s_nop 0
	v_cndmask_b32_e32 v28, v29, v28, vcc
	v_div_scale_f32 v29, s[2:3], v28, v28, 1.0
	v_rcp_f32_e32 v46, v29
	v_div_scale_f32 v47, vcc, 1.0, v28, 1.0
	v_fma_f32 v48, -v29, v46, 1.0
	v_fmac_f32_e32 v46, v48, v46
	v_mul_f32_e32 v48, v47, v46
	v_fma_f32 v49, -v29, v48, v47
	v_fmac_f32_e32 v48, v49, v46
	v_fma_f32 v29, -v29, v48, v47
	v_div_fmas_f32 v29, v29, v46, v48
	v_div_fixup_f32 v46, v29, v28, 1.0
	s_waitcnt vmcnt(11)
	v_lshlrev_b32_e32 v28, 16, v30
	v_and_b32_e32 v29, 0xffff0000, v30
	v_lshlrev_b32_e32 v30, 16, v31
	v_and_b32_e32 v31, 0xffff0000, v31
	v_lshlrev_b32_e32 v48, 16, v32
	v_and_b32_e32 v49, 0xffff0000, v32
	v_lshlrev_b32_e32 v32, 16, v33
	v_and_b32_e32 v33, 0xffff0000, v33
	v_pk_mul_f32 v[28:29], v[46:47], v[28:29] op_sel_hi:[0,1]
	v_pk_mul_f32 v[30:31], v[46:47], v[30:31] op_sel_hi:[0,1]
	v_pk_mul_f32 v[48:49], v[46:47], v[48:49] op_sel_hi:[0,1]
	v_pk_mul_f32 v[32:33], v[46:47], v[32:33] op_sel_hi:[0,1]
	s_waitcnt vmcnt(10)
	v_pk_mul_f32 v[30:31], v[36:37], v[30:31]
	v_pk_mul_f32 v[28:29], v[34:35], v[28:29]
	s_waitcnt vmcnt(9)
	v_pk_mul_f32 v[34:35], v[40:41], v[32:33]
	v_pk_mul_f32 v[32:33], v[38:39], v[48:49]
	global_store_dwordx4 v[44:45], v[28:31], off nt
	global_store_dwordx4 v[44:45], v[32:35], off offset:16 nt
	v_lshl_add_u64 v[40:41], s[10:11], 0, v[4:5]
	s_waitcnt vmcnt(10)
	v_mov_b32_e32 v28, v60
	v_mov_b32_e32 v29, v61
	v_mov_b32_e32 v30, v62
	v_mov_b32_e32 v31, v63
	v_lshlrev_b32_e32 v44, 16, v28
	v_and_b32_e32 v45, 0xffff0000, v28
	v_lshlrev_b32_e32 v28, 16, v29
	v_and_b32_e32 v29, 0xffff0000, v29
	v_lshlrev_b32_e32 v48, 16, v30
	v_and_b32_e32 v49, 0xffff0000, v30
	v_lshlrev_b32_e32 v30, 16, v31
	v_and_b32_e32 v31, 0xffff0000, v31
	v_pk_mul_f32 v[44:45], v[46:47], v[44:45] op_sel_hi:[0,1]
	v_pk_mul_f32 v[28:29], v[46:47], v[28:29] op_sel_hi:[0,1]
	v_pk_mul_f32 v[48:49], v[46:47], v[48:49] op_sel_hi:[0,1]
	v_pk_mul_f32 v[50:51], v[46:47], v[30:31] op_sel_hi:[0,1]
	s_waitcnt vmcnt(9)
	v_mov_b32_e32 v32, v64
	v_mov_b32_e32 v33, v65
	v_mov_b32_e32 v34, v66
	v_mov_b32_e32 v35, v67
	v_pk_mul_f32 v[30:31], v[34:35], v[28:29]
	v_pk_mul_f32 v[28:29], v[32:33], v[44:45]
	s_waitcnt vmcnt(8)
	v_mov_b32_e32 v36, v68
	v_mov_b32_e32 v37, v69
	v_mov_b32_e32 v38, v70
	v_mov_b32_e32 v39, v71
	v_pk_mul_f32 v[34:35], v[38:39], v[50:51]
	v_pk_mul_f32 v[32:33], v[36:37], v[48:49]
	global_store_dwordx4 v[40:41], v[28:31], off nt
	global_store_dwordx4 v[40:41], v[32:35], off offset:16 nt
	v_lshl_add_u64 v[40:41], s[10:11], 0, v[8:9]
	s_waitcnt vmcnt(9)
	v_mov_b32_e32 v28, v72
	v_mov_b32_e32 v29, v73
	v_mov_b32_e32 v30, v74
	v_mov_b32_e32 v31, v75
	v_lshlrev_b32_e32 v44, 16, v28
	v_and_b32_e32 v45, 0xffff0000, v28
	v_lshlrev_b32_e32 v28, 16, v29
	v_and_b32_e32 v29, 0xffff0000, v29
	v_lshlrev_b32_e32 v48, 16, v30
	v_and_b32_e32 v49, 0xffff0000, v30
	v_lshlrev_b32_e32 v30, 16, v31
	v_and_b32_e32 v31, 0xffff0000, v31
	v_pk_mul_f32 v[44:45], v[46:47], v[44:45] op_sel_hi:[0,1]
	v_pk_mul_f32 v[28:29], v[46:47], v[28:29] op_sel_hi:[0,1]
	v_pk_mul_f32 v[48:49], v[46:47], v[48:49] op_sel_hi:[0,1]
	v_pk_mul_f32 v[50:51], v[46:47], v[30:31] op_sel_hi:[0,1]
	s_waitcnt vmcnt(8)
	v_mov_b32_e32 v32, v76
	v_mov_b32_e32 v33, v77
	v_mov_b32_e32 v34, v78
	v_mov_b32_e32 v35, v79
	v_pk_mul_f32 v[30:31], v[34:35], v[28:29]
	v_pk_mul_f32 v[28:29], v[32:33], v[44:45]
	s_waitcnt vmcnt(7)
	v_mov_b32_e32 v36, v80
	v_mov_b32_e32 v37, v81
	v_mov_b32_e32 v38, v82
	v_mov_b32_e32 v39, v83
	v_pk_mul_f32 v[34:35], v[38:39], v[50:51]
	v_pk_mul_f32 v[32:33], v[36:37], v[48:49]
	global_store_dwordx4 v[40:41], v[28:31], off offset:-16 nt
	global_store_dwordx4 v[40:41], v[32:35], off nt
	v_lshl_add_u64 v[40:41], s[10:11], 0, v[12:13]
	s_add_u32 s10, s10, s12
	s_addc_u32 s11, s11, s13
	s_cmpk_lt_i32 s4, 0x6000
	s_waitcnt vmcnt(8)
	v_mov_b32_e32 v28, v84
	v_mov_b32_e32 v29, v85
	v_mov_b32_e32 v30, v86
	v_mov_b32_e32 v31, v87
	v_lshlrev_b32_e32 v42, 16, v28
	v_and_b32_e32 v43, 0xffff0000, v28
	v_lshlrev_b32_e32 v28, 16, v29
	v_and_b32_e32 v29, 0xffff0000, v29
	v_lshlrev_b32_e32 v44, 16, v30
	v_and_b32_e32 v45, 0xffff0000, v30
	v_lshlrev_b32_e32 v30, 16, v31
	v_and_b32_e32 v31, 0xffff0000, v31
	v_pk_mul_f32 v[42:43], v[46:47], v[42:43] op_sel_hi:[0,1]
	v_pk_mul_f32 v[28:29], v[46:47], v[28:29] op_sel_hi:[0,1]
	v_pk_mul_f32 v[44:45], v[46:47], v[44:45] op_sel_hi:[0,1]
	v_pk_mul_f32 v[46:47], v[46:47], v[30:31] op_sel_hi:[0,1]
	s_waitcnt vmcnt(7)
	v_mov_b32_e32 v32, v88
	v_mov_b32_e32 v33, v89
	v_mov_b32_e32 v34, v90
	v_mov_b32_e32 v35, v91
	v_pk_mul_f32 v[30:31], v[34:35], v[28:29]
	v_pk_mul_f32 v[28:29], v[32:33], v[42:43]
	s_waitcnt vmcnt(6)
	v_mov_b32_e32 v36, v92
	v_mov_b32_e32 v37, v93
	v_mov_b32_e32 v38, v94
	v_mov_b32_e32 v39, v95
	v_pk_mul_f32 v[34:35], v[38:39], v[46:47]
	v_pk_mul_f32 v[32:33], v[36:37], v[44:45]
	global_store_dwordx4 v[40:41], v[28:31], off offset:-16 nt
	global_store_dwordx4 v[40:41], v[32:35], off nt
	s_cbranch_scc0 .LBB0_636
